# v114 with a four-way prompt-item wave stagger: sleep = (wave>>2)*24 + (wave&1)*12 (x64 clocks) instead of waves 4-7 sleeping 24
# baseline (speedup 1.0000x reference)
; template <bool SAMPLE> ...
;     ...
;     for (int d0 = 0; d0 < 4; ++d0) { const f32x4 g0 = *(const f32x4*)(qg + d0 * 16 + hi * 8), g1 = *(const f32x4*)(qg + d0 * 16 + hi * 8 + 4);
;         q[d0][0] *= rstd * g0.x; q[d0][1] *= rstd * g0.y; q[d0][2] *= rstd * g0.z; q[d0][3] *= rstd * g0.w; q[d0][4] *= rstd * g1.x; q[d0][5] *= rstd * g1.y; q[d0][6] *= rstd * g1.z; q[d0][7] *= rstd * g1.w; }
; __device__ __forceinline__ void attn_prompt_item(const Args& a, int l, int item, LAS unsigned char* lds, int tid, int lane, int wave) {
;     ...
;     __syncthreads();
;     attn_tile32<false>(qw0, zw0, Y, tab, qg, sinks, Kl + 32 * qt0 * 144, Vl + 32 * qt0 * 64, 16384, wsf, ost, rowq0, headw, b * 128 + qt0 * 32, (b == 0) ? 4 - qt0 : 0, lane);
.LBB0_475:
	s_or_b64 exec, exec, s[0:1]
	v_cmp_lt_i32_e32 vcc, v220, v214
	v_and_b32_e32 v172, 32, v132
	s_waitcnt lgkmcnt(0)
	v_cndmask_b32_e32 v16, v213, v220, vcc
	s_barrier
	v_lshlrev_b32_e32 v127, 2, v16
	global_load_dwordx4 v[16:19], v172, s[62:63]
	global_load_dwordx4 v[20:23], v172, s[62:63] offset:16
	global_load_dwordx4 v[24:27], v172, s[62:63] offset:64
	global_load_dwordx4 v[28:31], v172, s[62:63] offset:80
	global_load_dwordx4 v[32:35], v172, s[62:63] offset:128
	global_load_dwordx4 v[36:39], v172, s[62:63] offset:144
	global_load_dwordx4 v[40:43], v172, s[62:63] offset:192
	global_load_dwordx4 v[44:47], v172, s[62:63] offset:208
	v_readfirstlane_b32 s0, v208
	s_nop 3
	s_bitcmp1_b32 s0, 8
	s_cbranch_scc0 .Lstg_lo
	s_sleep 24
.Lstg_lo:
	s_bitcmp1_b32 s0, 6
	s_cbranch_scc0 .Lstg_skip
	s_sleep 12
